# attention and memory-attention unit epilogue: 8 dwordx2 stores per lane widened to 4 dwordx4 via v_permlane32_swap pairs
# baseline (speedup 1.0000x reference)
.LBB0_1006:
	s_waitcnt lgkmcnt(0)
	v_add_f32_e32 v32, v179, v32
	v_div_scale_f32 v33, s[6:7], v32, v32, 1.0
	v_rcp_f32_e32 v34, v33
	s_lshl_b32 s4, s51, 6
	s_ashr_i32 s5, s4, 31
	s_lshl_b64 s[4:5], s[4:5], 1
	v_fma_f32 v35, -v33, v34, 1.0
	v_fmac_f32_e32 v34, v35, v34
	v_div_scale_f32 v35, vcc, 1.0, v32, 1.0
	v_mul_f32_e32 v36, v35, v34
	v_fma_f32 v37, -v33, v36, v35
	v_fmac_f32_e32 v36, v37, v34
	s_add_u32 s4, s34, s4
	v_fma_f32 v33, -v33, v36, v35
	s_addc_u32 s5, s35, s5
	v_div_fmas_f32 v33, v33, v34, v36
	v_lshlrev_b64 v[34:35], 11, v[166:167]
	v_div_fixup_f32 v32, v33, v32, 1.0
	v_lshl_add_u64 v[34:35], s[4:5], 0, v[34:35]
	v_lshlrev_b32_e32 v112, 4, v175
	v_lshl_add_u64 v[34:35], v[34:35], 0, v[112:113]
	s_mov_b64 s[4:5], 0x10200000
	v_lshl_add_u64 v[36:37], v[34:35], 0, s[4:5]
	v_pk_mul_f32 v[16:17], v[32:33], v[16:17] op_sel_hi:[0,1]
	v_pk_mul_f32 v[18:19], v[32:33], v[18:19] op_sel_hi:[0,1]
	v_pk_mul_f32 v[20:21], v[32:33], v[20:21] op_sel_hi:[0,1]
	v_pk_mul_f32 v[22:23], v[32:33], v[22:23] op_sel_hi:[0,1]
	v_cvt_pk_bf16_f32 v16, v16, v17
	v_cvt_pk_bf16_f32 v17, v18, v19
	v_cvt_pk_bf16_f32 v18, v20, v21
	v_cvt_pk_bf16_f32 v19, v22, v23
	v_readlane_b32 s3, v255, 13
	s_add_i32 s50, s50, s3
	v_permlane32_swap_b32 v16, v18
	v_permlane32_swap_b32 v17, v19
	global_store_dwordx4 v[36:37], v[16:19], off
	v_pk_mul_f32 v[24:25], v[32:33], v[24:25] op_sel_hi:[0,1]
	v_pk_mul_f32 v[26:27], v[32:33], v[26:27] op_sel_hi:[0,1]
	v_pk_mul_f32 v[28:29], v[32:33], v[28:29] op_sel_hi:[0,1]
	v_pk_mul_f32 v[30:31], v[32:33], v[30:31] op_sel_hi:[0,1]
	v_cvt_pk_bf16_f32 v24, v24, v25
	v_cvt_pk_bf16_f32 v25, v26, v27
	v_cvt_pk_bf16_f32 v26, v28, v29
	v_cvt_pk_bf16_f32 v27, v30, v31
	v_readlane_b32 s62, v255, 36
	s_cmpk_gt_i32 s50, 0xbf
	v_permlane32_swap_b32 v24, v26
	v_permlane32_swap_b32 v25, v27
	global_store_dwordx4 v[36:37], v[24:27], off offset:32
	v_pk_mul_f32 v[0:1], v[32:33], v[0:1] op_sel_hi:[0,1]
	v_pk_mul_f32 v[2:3], v[32:33], v[2:3] op_sel_hi:[0,1]
	v_pk_mul_f32 v[4:5], v[32:33], v[4:5] op_sel_hi:[0,1]
	v_pk_mul_f32 v[6:7], v[32:33], v[6:7] op_sel_hi:[0,1]
	v_cvt_pk_bf16_f32 v0, v0, v1
	v_cvt_pk_bf16_f32 v1, v2, v3
	v_cvt_pk_bf16_f32 v2, v4, v5
	v_cvt_pk_bf16_f32 v3, v6, v7
	s_movk_i32 s47, 0x180
	v_readlane_b32 s63, v255, 37
	v_permlane32_swap_b32 v0, v2
	v_permlane32_swap_b32 v1, v3
	global_store_dwordx4 v[36:37], v[0:3], off offset:64
	v_pk_mul_f32 v[8:9], v[32:33], v[8:9] op_sel_hi:[0,1]
	v_pk_mul_f32 v[10:11], v[32:33], v[10:11] op_sel_hi:[0,1]
	v_pk_mul_f32 v[12:13], v[32:33], v[12:13] op_sel_hi:[0,1]
	v_pk_mul_f32 v[14:15], v[32:33], v[14:15] op_sel_hi:[0,1]
	v_cvt_pk_bf16_f32 v8, v8, v9
	v_cvt_pk_bf16_f32 v9, v10, v11
	v_cvt_pk_bf16_f32 v10, v12, v13
	v_cvt_pk_bf16_f32 v11, v14, v15
	s_nop 1
	v_permlane32_swap_b32 v8, v10
	v_permlane32_swap_b32 v9, v11
	global_store_dwordx4 v[36:37], v[8:11], off offset:96
	s_cbranch_scc1 .LBB0_1058

.LBB0_1256:
	s_waitcnt lgkmcnt(0)
	v_add_f32_e32 v32, v147, v32
	v_div_scale_f32 v33, s[6:7], v32, v32, 1.0
	v_rcp_f32_e32 v34, v33
	s_lshl_b32 s4, s31, 6
	s_lshl_b32 s3, s4, 1
	s_add_u32 s4, s12, s3
	v_fma_f32 v35, -v33, v34, 1.0
	v_fmac_f32_e32 v34, v35, v34
	v_div_scale_f32 v35, vcc, 1.0, v32, 1.0
	v_mul_f32_e32 v36, v35, v34
	v_fma_f32 v37, -v33, v36, v35
	v_fmac_f32_e32 v36, v37, v34
	v_fma_f32 v33, -v33, v36, v35
	s_addc_u32 s5, s13, 0
	v_div_fmas_f32 v33, v33, v34, v36
	v_lshlrev_b64 v[34:35], 11, v[156:157]
	v_div_fixup_f32 v32, v33, v32, 1.0
	v_lshl_add_u64 v[34:35], s[4:5], 0, v[34:35]
	v_lshlrev_b32_e32 v112, 4, v158
	v_lshl_add_u64 v[34:35], v[34:35], 0, v[112:113]
	s_mov_b64 s[4:5], 0x10200600
	v_lshl_add_u64 v[36:37], v[34:35], 0, s[4:5]
	v_pk_mul_f32 v[16:17], v[32:33], v[16:17] op_sel_hi:[0,1]
	v_pk_mul_f32 v[18:19], v[32:33], v[18:19] op_sel_hi:[0,1]
	v_pk_mul_f32 v[20:21], v[32:33], v[20:21] op_sel_hi:[0,1]
	v_pk_mul_f32 v[22:23], v[32:33], v[22:23] op_sel_hi:[0,1]
	v_cvt_pk_bf16_f32 v16, v16, v17
	v_cvt_pk_bf16_f32 v17, v18, v19
	v_cvt_pk_bf16_f32 v18, v20, v21
	v_cvt_pk_bf16_f32 v19, v22, v23
	s_add_i32 s30, s30, s26
	s_cmpk_gt_i32 s30, 0x1ff
	v_permlane32_swap_b32 v16, v18
	v_permlane32_swap_b32 v17, v19
	global_store_dwordx4 v[36:37], v[16:19], off
	v_pk_mul_f32 v[24:25], v[32:33], v[24:25] op_sel_hi:[0,1]
	v_pk_mul_f32 v[26:27], v[32:33], v[26:27] op_sel_hi:[0,1]
	v_pk_mul_f32 v[28:29], v[32:33], v[28:29] op_sel_hi:[0,1]
	v_pk_mul_f32 v[30:31], v[32:33], v[30:31] op_sel_hi:[0,1]
	v_cvt_pk_bf16_f32 v24, v24, v25
	v_cvt_pk_bf16_f32 v25, v26, v27
	v_cvt_pk_bf16_f32 v26, v28, v29
	v_cvt_pk_bf16_f32 v27, v30, v31
	s_nop 1
	v_permlane32_swap_b32 v24, v26
	v_permlane32_swap_b32 v25, v27
	global_store_dwordx4 v[36:37], v[24:27], off offset:32
	v_pk_mul_f32 v[0:1], v[32:33], v[0:1] op_sel_hi:[0,1]
	v_pk_mul_f32 v[2:3], v[32:33], v[2:3] op_sel_hi:[0,1]
	v_pk_mul_f32 v[4:5], v[32:33], v[4:5] op_sel_hi:[0,1]
	v_pk_mul_f32 v[6:7], v[32:33], v[6:7] op_sel_hi:[0,1]
	v_cvt_pk_bf16_f32 v0, v0, v1
	v_cvt_pk_bf16_f32 v1, v2, v3
	v_cvt_pk_bf16_f32 v2, v4, v5
	v_cvt_pk_bf16_f32 v3, v6, v7
	s_nop 1
	v_permlane32_swap_b32 v0, v2
	v_permlane32_swap_b32 v1, v3
	global_store_dwordx4 v[36:37], v[0:3], off offset:64
	v_pk_mul_f32 v[8:9], v[32:33], v[8:9] op_sel_hi:[0,1]
	v_pk_mul_f32 v[10:11], v[32:33], v[10:11] op_sel_hi:[0,1]
	v_pk_mul_f32 v[12:13], v[32:33], v[12:13] op_sel_hi:[0,1]
	v_pk_mul_f32 v[14:15], v[32:33], v[14:15] op_sel_hi:[0,1]
	v_cvt_pk_bf16_f32 v8, v8, v9
	v_cvt_pk_bf16_f32 v9, v10, v11
	v_cvt_pk_bf16_f32 v10, v12, v13
	v_cvt_pk_bf16_f32 v11, v14, v15
	s_nop 1
	v_permlane32_swap_b32 v8, v10
	v_permlane32_swap_b32 v9, v11
	global_store_dwordx4 v[36:37], v[8:11], off offset:96
	s_cbranch_scc1 .LBB0_1314
